# v28 + MLA K/rope-K fragment read bases re-biased so both ring slots use immediate ds offsets (12 fewer VALU adds per 2 tiles)
# baseline (speedup 1.0000x reference)
.LBB0_537:
	s_and_b32 s2, s85, 7
	s_mul_hi_i32 s3, s4, 0x1e00
	s_mulk_i32 s4, 0x1e00
	s_add_u32 s4, s54, s4
	s_addc_u32 s3, s55, s3
	s_lshl_b32 s5, s2, 7
	s_lshl_b32 s17, s2, 8
	v_mov_b32_e32 v172, v184
	s_waitcnt lgkmcnt(0)
	s_barrier
	s_add_u32 s60, s4, s17
	s_addc_u32 s61, s3, 0
	v_ashrrev_i32_e32 v167, 6, v172
	v_and_b32_e32 v168, 31, v172
	v_and_b32_e32 v2, 0x3fffffc0, v172
	v_lshlrev_b32_e32 v166, 5, v167
	v_bfe_u32 v169, v172, 5, 1
	v_lshl_add_u32 v51, v2, 2, s41
	v_or_b32_e32 v4, v166, v168
	v_mov_b64_e32 v[2:3], s[60:61]
	v_mad_i64_i32 v[2:3], s[20:21], v4, s35, v[2:3]
	v_lshlrev_b32_e32 v158, 4, v169
	v_lshl_add_u64 v[2:3], v[2:3], 0, v[158:159]
	global_load_dwordx4 v[142:145], v[2:3], off offset:2048
	global_load_dwordx4 v[138:141], v[2:3], off offset:2080
	global_load_dwordx4 v[134:137], v[2:3], off offset:2112
	global_load_dwordx4 v[130:133], v[2:3], off offset:2144
	global_load_dwordx4 v[126:129], v[2:3], off offset:2176
	global_load_dwordx4 v[122:125], v[2:3], off offset:2208
	global_load_dwordx4 v[118:121], v[2:3], off offset:2240
	global_load_dwordx4 v[114:117], v[2:3], off offset:2272
	s_add_u32 s4, s4, s5
	s_addc_u32 s3, s3, 0
	s_add_u32 s18, s4, 0x1400
	s_addc_u32 s19, s3, 0
	v_mov_b64_e32 v[2:3], s[18:19]
	s_lshl_b64 s[4:5], s[0:1], 12
	v_mad_i64_i32 v[2:3], s[18:19], v4, s35, v[2:3]
	s_add_u32 s3, s88, s4
	v_lshl_add_u64 v[2:3], v[2:3], 0, v[158:159]
	v_mov_b32_e32 v8, v172
	s_addc_u32 s17, s89, s5
	s_lshl_b32 s2, s2, 9
	global_load_dwordx4 v[110:113], v[2:3], off
	global_load_dwordx4 v[106:109], v[2:3], off offset:32
	global_load_dwordx4 v[102:105], v[2:3], off offset:64
	global_load_dwordx4 v[98:101], v[2:3], off offset:96
	s_add_u32 s2, s3, s2
	v_ashrrev_i32_e32 v3, 4, v8
	v_bfe_u32 v5, v8, 2, 2
	v_lshlrev_b32_e32 v2, 11, v3
	v_xor_b32_e32 v4, v3, v8
	v_and_or_b32 v5, v3, s75, v5
	v_lshrrev_b32_e32 v6, 1, v8
	v_lshrrev_b32_e32 v3, 1, v3
	s_addc_u32 s3, s17, 0
	s_mulk_i32 s1, 0x1e00
	s_mul_hi_u32 s17, s0, 0x1e00
	v_and_b32_e32 v6, 8, v6
	v_and_b32_e32 v3, 4, v3
	s_add_i32 s87, s17, s1
	s_mul_i32 s88, s0, 0x1e00
	v_lshlrev_b32_e32 v4, 3, v4
	v_or3_b32 v3, v5, v6, v3
	v_lshlrev_b32_e32 v5, 3, v8
	s_add_u32 s0, s54, s88
	v_readfirstlane_b32 s17, v167
	v_and_or_b32 v2, v4, s74, v2
	v_and_b32_e32 v4, 0x60, v8
	v_lshlrev_b32_e32 v3, 11, v3
	v_and_b32_e32 v5, 24, v5
	s_addc_u32 s1, s55, s87
	s_lshl_b32 s17, s17, 10
	v_or3_b32 v4, v3, v4, v5
	v_ashrrev_i32_e32 v5, 31, v4
	s_add_i32 s89, s17, 0
	v_ashrrev_i32_e32 v3, 31, v2
	v_lshl_add_u64 v[4:5], v[4:5], 1, s[2:3]
	s_mov_b64 s[18:19], 0x100
	s_add_i32 s90, s89, 0xc000
	v_lshl_add_u64 v[2:3], v[2:3], 1, s[2:3]
	v_lshl_add_u64 v[6:7], v[4:5], 0, s[18:19]
	s_mov_b32 m0, s90
	s_mov_b64 s[18:19], 0x20000
	s_add_i32 s91, s89, 0xe000
	global_load_lds_dwordx4 v[2:3], off
	v_lshl_add_u64 v[2:3], v[2:3], 0, s[18:19]
	s_mov_b32 m0, s91
	s_mov_b64 s[18:19], 0x20100
	global_load_lds_dwordx4 v[2:3], off
	s_mov_b32 m0, s89
	v_lshl_add_u64 v[2:3], v[4:5], 0, s[18:19]
	global_load_lds_dwordx4 v[6:7], off
	s_add_i32 m0, s89, 0x2000
	s_mov_b64 s[18:19], 0x1c00
	global_load_lds_dwordx4 v[2:3], off
	v_lshrrev_b32_e32 v3, 4, v8
	v_lshrrev_b32_e32 v2, 3, v8
	v_xor_b32_e32 v3, v3, v8
	v_mul_lo_u32 v2, v2, s76
	v_lshlrev_b32_e32 v3, 3, v3
	v_and_or_b32 v2, v3, 56, v2
	v_ashrrev_i32_e32 v3, 31, v2
	v_lshl_add_u64 v[2:3], v[2:3], 1, s[0:1]
	s_add_i32 s92, s89, 0x14000
	v_lshl_add_u64 v[2:3], v[2:3], 0, s[18:19]
	s_mov_b32 m0, s92
	v_mov_b32_e32 v10, v172
	global_load_lds_dwordx4 v[2:3], off
	s_waitcnt vmcnt(0)
	s_waitcnt vmcnt(0) lgkmcnt(0)
	s_barrier
	s_mov_b64 s[18:19], 0x40000
	v_ashrrev_i32_e32 v3, 4, v10
	v_bfe_u32 v5, v10, 2, 2
	v_lshlrev_b32_e32 v2, 11, v3
	v_xor_b32_e32 v4, v3, v10
	v_and_or_b32 v5, v3, s75, v5
	v_lshrrev_b32_e32 v6, 1, v10
	v_lshrrev_b32_e32 v3, 1, v3
	v_and_b32_e32 v6, 8, v6
	v_and_b32_e32 v3, 4, v3
	v_lshlrev_b32_e32 v4, 3, v4
	v_or3_b32 v3, v5, v6, v3
	v_lshlrev_b32_e32 v5, 3, v10
	v_and_or_b32 v2, v4, s74, v2
	v_and_b32_e32 v4, 0x60, v10
	v_lshlrev_b32_e32 v3, 11, v3
	v_and_b32_e32 v5, 24, v5
	v_or3_b32 v4, v3, v4, v5
	v_ashrrev_i32_e32 v3, 31, v2
	v_ashrrev_i32_e32 v5, 31, v4
	v_lshl_add_u64 v[2:3], v[2:3], 1, s[2:3]
	v_lshl_add_u64 v[4:5], v[4:5], 1, s[2:3]
	s_mov_b64 s[2:3], 0x40100
	s_add_i32 s93, s89, 0x10000
	v_lshl_add_u64 v[6:7], v[2:3], 0, s[18:19]
	v_lshl_add_u64 v[8:9], v[4:5], 0, s[2:3]
	s_mov_b32 m0, s93
	s_mov_b64 s[2:3], 0x60000
	s_add_i32 s94, s89, 0x12000
	global_load_lds_dwordx4 v[6:7], off
	v_lshl_add_u64 v[2:3], v[2:3], 0, s[2:3]
	s_mov_b32 m0, s94
	s_mov_b64 s[2:3], 0x60100
	global_load_lds_dwordx4 v[2:3], off
	s_add_i32 m0, s89, 0x4000
	v_lshl_add_u64 v[2:3], v[4:5], 0, s[2:3]
	global_load_lds_dwordx4 v[8:9], off
	s_add_i32 m0, s89, 0x6000
	s_add_i32 s95, s89, 0x16000
	global_load_lds_dwordx4 v[2:3], off
	v_lshrrev_b32_e32 v3, 4, v10
	v_lshrrev_b32_e32 v2, 3, v10
	v_xor_b32_e32 v3, v3, v10
	v_mul_lo_u32 v2, v2, s76
	v_lshlrev_b32_e32 v3, 3, v3
	v_and_or_b32 v2, v3, 56, v2
	v_ashrrev_i32_e32 v3, 31, v2
	v_lshl_add_u64 v[2:3], v[2:3], 1, s[0:1]
	s_mov_b64 s[0:1], 0x79c00
	v_lshl_add_u64 v[2:3], v[2:3], 0, s[0:1]
	s_mov_b32 m0, s95
	v_lshlrev_b32_e32 v10, 8, v168
	global_load_lds_dwordx4 v[2:3], off
	v_lshlrev_b32_e32 v2, 4, v172
	v_and_b32_e32 v160, 0xf0, v2
	v_bitop3_b32 v173, v158, v10, v160 bitop3:0xde
	v_add_u32_e32 v174, 0x4000, v173
	ds_read_b128 v[2:5], v174 offset:32768
	ds_read_b128 v[6:9], v174 offset:40960
	s_waitcnt lgkmcnt(0)
	v_mfma_f32_32x32x16_bf16 v[34:49], v[2:5], v[142:145], 0
	v_or_b32_e32 v11, 32, v158
	v_bitop3_b32 v175, v11, v10, v160 bitop3:0xde
	v_add_u32_e32 v176, 0x4000, v175
	v_or_b32_e32 v12, 64, v158
	v_bitop3_b32 v177, v12, v10, v160 bitop3:0xde
	v_add_u32_e32 v178, 0x4000, v177
	v_or_b32_e32 v13, 0x60, v158
	v_mfma_f32_32x32x16_bf16 v[18:33], v[6:9], v[142:145], 0
	ds_read_b128 v[2:5], v176 offset:32768
	ds_read_b128 v[6:9], v176 offset:40960
	v_bitop3_b32 v179, v13, v10, v160 bitop3:0xde
	v_add_u32_e32 v180, 0x4000, v179
	s_add_i32 s0, 0, 0x14000
	v_and_b32_e32 v161, 63, v172
	v_lshlrev_b32_e32 v52, 2, v169
	s_waitcnt lgkmcnt(0)
	v_mfma_f32_32x32x16_bf16 v[34:49], v[2:5], v[138:141], v[34:49]
	v_mfma_f32_32x32x16_bf16 v[18:33], v[6:9], v[138:141], v[18:33]
	ds_read_b128 v[2:5], v178 offset:32768
	ds_read_b128 v[6:9], v178 offset:40960
	s_waitcnt lgkmcnt(0)
	v_mfma_f32_32x32x16_bf16 v[34:49], v[2:5], v[134:137], v[34:49]
	v_mfma_f32_32x32x16_bf16 v[18:33], v[6:9], v[134:137], v[18:33]
	ds_read_b128 v[2:5], v180 offset:32768
	ds_read_b128 v[6:9], v180 offset:40960
	s_waitcnt lgkmcnt(0)
	v_mfma_f32_32x32x16_bf16 v[34:49], v[2:5], v[130:133], v[34:49]
	v_or_b32_e32 v2, 0x80, v158
	v_bitop3_b32 v181, v2, v10, v160 bitop3:0xde
	v_add_u32_e32 v182, 0x4000, v181
	v_mfma_f32_32x32x16_bf16 v[18:33], v[6:9], v[130:133], v[18:33]
	ds_read_b128 v[2:5], v182 offset:32768
	ds_read_b128 v[6:9], v182 offset:40960
	s_waitcnt lgkmcnt(0)
	v_mfma_f32_32x32x16_bf16 v[34:49], v[2:5], v[126:129], v[34:49]
	v_or_b32_e32 v2, 0xa0, v158
	v_bitop3_b32 v183, v2, v10, v160 bitop3:0xde
	v_add_u32_e32 v186, 0x4000, v183
	v_mfma_f32_32x32x16_bf16 v[18:33], v[6:9], v[126:129], v[18:33]
	ds_read_b128 v[2:5], v186 offset:32768
	ds_read_b128 v[6:9], v186 offset:40960
	s_waitcnt lgkmcnt(0)
	v_mfma_f32_32x32x16_bf16 v[34:49], v[2:5], v[122:125], v[34:49]
	v_or_b32_e32 v2, 0xc0, v158
	v_bitop3_b32 v187, v2, v10, v160 bitop3:0xde
	v_add_u32_e32 v188, 0x4000, v187
	v_mfma_f32_32x32x16_bf16 v[18:33], v[6:9], v[122:125], v[18:33]
	ds_read_b128 v[2:5], v188 offset:32768
	ds_read_b128 v[6:9], v188 offset:40960
	s_waitcnt lgkmcnt(0)
	v_mfma_f32_32x32x16_bf16 v[34:49], v[2:5], v[118:121], v[34:49]
	v_or_b32_e32 v2, 0xe0, v158
	v_bitop3_b32 v189, v2, v10, v160 bitop3:0xde
	v_add_u32_e32 v190, 0x4000, v189
	v_lshlrev_b32_e32 v10, 7, v168
	v_mfma_f32_32x32x16_bf16 v[18:33], v[6:9], v[118:121], v[18:33]
	ds_read_b128 v[2:5], v190 offset:32768
	ds_read_b128 v[6:9], v190 offset:40960
	s_waitcnt lgkmcnt(0)
	v_mfma_f32_32x32x16_bf16 v[34:49], v[2:5], v[114:117], v[34:49]
	v_lshlrev_b32_e32 v2, 3, v172
	v_and_b32_e32 v14, 0x70, v2
	v_bitop3_b32 v191, v158, v10, v14 bitop3:0xde
	v_add_u32_e32 v192, s0, v191
	v_bitop3_b32 v193, v11, v10, v14 bitop3:0xde
	v_add_u32_e32 v194, s0, v193
	v_bitop3_b32 v195, v12, v10, v14 bitop3:0xde
	v_mfma_f32_32x32x16_bf16 v[18:33], v[6:9], v[114:117], v[18:33]
	ds_read_b128 v[2:5], v192
	ds_read_b128 v[6:9], v192 offset:4096
	v_add_u32_e32 v196, s0, v195
	v_bitop3_b32 v198, v13, v10, v14 bitop3:0xde
	v_add_u32_e32 v199, s0, v198
	v_cmp_gt_u32_e64 s[0:1], 32, v161
	s_waitcnt lgkmcnt(0)
	v_mfma_f32_32x32x16_bf16 v[34:49], v[2:5], v[110:113], v[34:49]
	v_mfma_f32_32x32x16_bf16 v[18:33], v[6:9], v[110:113], v[18:33]
	ds_read_b128 v[2:5], v194
	ds_read_b128 v[6:9], v194 offset:4096
	s_waitcnt lgkmcnt(0)
	v_mfma_f32_32x32x16_bf16 v[34:49], v[2:5], v[106:109], v[34:49]
	v_mfma_f32_32x32x16_bf16 v[18:33], v[6:9], v[106:109], v[18:33]
	ds_read_b128 v[2:5], v196
	ds_read_b128 v[6:9], v196 offset:4096
	s_waitcnt lgkmcnt(0)
	v_mfma_f32_32x32x16_bf16 v[34:49], v[2:5], v[102:105], v[34:49]
	v_mfma_f32_32x32x16_bf16 v[18:33], v[6:9], v[102:105], v[18:33]
	ds_read_b128 v[2:5], v199
	ds_read_b128 v[6:9], v199 offset:4096
	s_waitcnt lgkmcnt(0)
	v_mfma_f32_32x32x16_bf16 v[34:49], v[2:5], v[98:101], v[34:49]
	v_mfma_f32_32x32x16_bf16 v[18:33], v[6:9], v[98:101], v[18:33]
	s_nop 10
	v_max_f32_e32 v2, v35, v35
	v_max_f32_e32 v3, v34, v34
	v_max_f32_e32 v2, v3, v2
	v_max3_f32 v2, v2, v36, v37
	v_max3_f32 v2, v2, v38, v39
	v_max3_f32 v2, v2, v40, v41
	v_max3_f32 v2, v2, v42, v43
	v_max3_f32 v2, v2, v44, v45
	v_max3_f32 v2, v2, v46, v47
	v_max3_f32 v2, v2, v48, v49
	v_max3_f32 v2, v2, v18, v19
	v_max3_f32 v2, v2, v20, v21
	v_max3_f32 v2, v2, v22, v23
	v_max3_f32 v2, v2, v24, v25
	v_max3_f32 v2, v2, v26, v27
	v_max3_f32 v2, v2, v28, v29
	v_max3_f32 v2, v2, v30, v31
	v_max3_f32 v2, v2, v32, v33
	v_mov_b32_e32 v3, v2
	s_nop 1
	v_permlane32_swap_b32_e32 v2, v3
	v_max_f32_e32 v3, v3, v3
	v_max_f32_e32 v2, v2, v2
	v_max_f32_e32 v2, v2, v3
	v_max_f32_e32 v50, 0xf149f2ca, v2
	v_add_f32_e32 v3, 0x7149f2ca, v2
	v_sub_f32_e32 v2, 0xf149f2ca, v50
	v_mul_f32_e32 v2, 0x3dd53b94, v2
	v_exp_f32_e32 v2, v2
	v_cmp_ge_f32_e32 vcc, s77, v3
	s_cmp_eq_u64 vcc, exec
	s_cselect_b64 s[2:3], -1, 0
	v_cndmask_b32_e64 v201, v2, 1.0, s[2:3]
	v_cmp_gt_f32_e32 vcc, 1.0, v201
	s_cbranch_vccz .LBB0_541
	s_and_saveexec_b64 s[18:19], s[0:1]
	v_lshl_add_u32 v2, v168, 2, v51
	ds_write_b32 v2, v201 offset:128
	s_or_b64 exec, exec, s[18:19]
	s_waitcnt lgkmcnt(0)
	v_lshl_add_u32 v10, v52, 2, v51
	ds_read_b128 v[2:5], v10 offset:224
	ds_read_b128 v[6:9], v10 offset:192
	ds_read_b128 v[54:57], v10 offset:160
	ds_read_b128 v[58:61], v10 offset:128
	s_waitcnt lgkmcnt(0)
	v_pk_mul_f32 v[16:17], v[4:5], 0 op_sel_hi:[1,0]
	v_pk_mul_f32 v[12:13], v[8:9], 0 op_sel_hi:[1,0]
	v_pk_mul_f32 v[8:9], v[56:57], 0 op_sel_hi:[1,0]
	v_pk_mul_f32 v[4:5], v[60:61], 0 op_sel_hi:[1,0]
	v_pk_mul_f32 v[14:15], v[2:3], 0 op_sel_hi:[1,0]
	v_pk_mul_f32 v[10:11], v[6:7], 0 op_sel_hi:[1,0]
	v_pk_mul_f32 v[6:7], v[54:55], 0 op_sel_hi:[1,0]
	v_pk_mul_f32 v[2:3], v[58:59], 0 op_sel_hi:[1,0]
	s_branch .LBB0_542

.LBB0_543:
	s_mov_b32 s23, s17
	s_mov_b32 s17, s0
	s_add_i32 s71, 0, 0x10000
	ds_read_b128 v[66:69], v174 offset:49152
	ds_read_b128 v[70:73], v174 offset:57344
	ds_read_b128 v[206:209], v176 offset:49152
	ds_read_b128 v[210:213], v176 offset:57344
	s_waitcnt lgkmcnt(0)
	v_mfma_f32_32x32x16_bf16 v[82:97], v[66:69], v[142:145], 0
	s_add_i32 s0, 0, 0x16000
	v_exp_f32_e32 v240, v146
	v_add_f32_e32 v146, 0, v229
	v_add_f32_e32 v146, v231, v146
	v_add_f32_e32 v146, v227, v146
	v_add_f32_e32 v146, v230, v146
	v_add_f32_e32 v146, v226, v146
	v_mfma_f32_32x32x16_bf16 v[66:81], v[70:73], v[142:145], 0
	v_add_f32_e32 v146, v228, v146
	v_add_f32_e32 v146, v224, v146
	v_add_f32_e32 v146, v225, v146
	v_add_f32_e32 v146, v221, v146
	v_add_f32_e32 v146, v223, v146
	v_add_f32_e32 v146, v220, v146
	v_add_f32_e32 v146, v222, v146
	v_mfma_f32_32x32x16_bf16 v[82:97], v[206:209], v[138:141], v[82:97]
	v_exp_f32_e32 v164, v164
	v_add_f32_e32 v146, v217, v146
	v_exp_f32_e32 v165, v165
	v_add_f32_e32 v146, v219, v146
	v_exp_f32_e32 v197, v162
	v_add_f32_e32 v146, v216, v146
	v_add_f32_e32 v146, v218, v146
	v_mfma_f32_32x32x16_bf16 v[66:81], v[210:213], v[138:141], v[66:81]
	ds_read_b128 v[206:209], v178 offset:49152
	ds_read_b128 v[210:213], v178 offset:57344
	s_add_u32 s4, s38, s20
	s_addc_u32 s5, s39, s21
	s_add_u32 s24, s4, 0x149ec400
	s_addc_u32 s25, s5, 0
	s_mov_b32 m0, s90
	v_lshl_add_u64 v[254:255], v[246:247], 0, s[24:25]
	s_lshl_b32 s18, s22, 14
	global_load_lds_dwordx4 v[254:255], off
	s_add_u32 s24, s4, 0x14a0c400
	s_addc_u32 s25, s5, 0
	s_mov_b32 m0, s91
	v_lshl_add_u64 v[254:255], v[246:247], 0, s[24:25]
	s_add_i32 s1, s89, s18
	global_load_lds_dwordx4 v[254:255], off
	s_add_u32 s24, s4, 0x149ec500
	s_addc_u32 s25, s5, 0
	s_mov_b32 m0, s1
	v_lshl_add_u64 v[254:255], v[248:249], 0, s[24:25]
	global_load_lds_dwordx4 v[254:255], off
	s_add_u32 s24, s4, 0x14a0c500
	s_addc_u32 s25, s5, 0
	s_add_i32 m0, s1, 0x2000
	v_lshl_add_u64 v[254:255], v[248:249], 0, s[24:25]
	global_load_lds_dwordx4 v[254:255], off
	s_add_u32 s4, s38, s88
	s_addc_u32 s5, s39, s87
	s_add_u32 s4, s4, s36
	s_addc_u32 s5, s5, s37
	s_mov_b32 m0, s92
	v_lshl_add_u64 v[254:255], v[250:251], 0, s[4:5]
	global_load_lds_dwordx4 v[254:255], off
	v_exp_f32_e32 v156, v156
	v_add_f32_e32 v146, v164, v146
	v_exp_f32_e32 v157, v157
	v_add_f32_e32 v146, v165, v146
	v_add_f32_e32 v146, v197, v146
	v_exp_f32_e32 v241, v147
	s_waitcnt lgkmcnt(0)
	v_mfma_f32_32x32x16_bf16 v[82:97], v[206:209], v[134:137], v[82:97]
	v_mfma_f32_32x32x16_bf16 v[66:81], v[210:213], v[134:137], v[66:81]
	ds_read_b128 v[208:211], v180 offset:49152
	ds_read_b128 v[212:215], v180 offset:57344
	s_waitcnt lgkmcnt(0)
	v_mfma_f32_32x32x16_bf16 v[82:97], v[208:211], v[130:133], v[82:97]
	v_mfma_f32_32x32x16_bf16 v[66:81], v[212:215], v[130:133], v[66:81]
	ds_read_b128 v[208:211], v182 offset:49152
	ds_read_b128 v[212:215], v182 offset:57344
	s_waitcnt lgkmcnt(0)
	v_mfma_f32_32x32x16_bf16 v[82:97], v[208:211], v[126:129], v[82:97]
	v_mfma_f32_32x32x16_bf16 v[66:81], v[212:215], v[126:129], v[66:81]
	ds_read_b128 v[210:213], v186 offset:49152
	ds_read_b128 v[232:235], v186 offset:57344
	s_waitcnt lgkmcnt(0)
	v_mfma_f32_32x32x16_bf16 v[82:97], v[210:213], v[122:125], v[82:97]
	v_mfma_f32_32x32x16_bf16 v[66:81], v[232:235], v[122:125], v[66:81]
	ds_read_b128 v[210:213], v188 offset:49152
	ds_read_b128 v[232:235], v188 offset:57344
	s_waitcnt lgkmcnt(0)
	v_mfma_f32_32x32x16_bf16 v[82:97], v[210:213], v[118:121], v[82:97]
	v_mfma_f32_32x32x16_bf16 v[66:81], v[232:235], v[118:121], v[66:81]
	ds_read_b128 v[212:215], v190 offset:49152
	ds_read_b128 v[232:235], v190 offset:57344
	s_waitcnt lgkmcnt(0)
	v_mfma_f32_32x32x16_bf16 v[82:97], v[212:215], v[114:117], v[82:97]
	v_mfma_f32_32x32x16_bf16 v[66:81], v[232:235], v[114:117], v[66:81]
	ds_read_b128 v[212:215], v192 offset:8192
	ds_read_b128 v[232:235], v192 offset:12288
	s_waitcnt lgkmcnt(0)
	v_mfma_f32_32x32x16_bf16 v[82:97], v[212:215], v[110:113], v[82:97]
	v_exp_f32_e32 v215, v163
	s_nop 0
	v_add_f32_e32 v146, v215, v146
	v_mfma_f32_32x32x16_bf16 v[66:81], v[232:235], v[110:113], v[66:81]
	ds_read_b128 v[232:235], v194 offset:8192
	ds_read_b128 v[236:239], v194 offset:12288
	v_add_f32_e32 v146, v156, v146
	v_add_f32_e32 v146, v157, v146
	s_waitcnt lgkmcnt(0)
	v_mfma_f32_32x32x16_bf16 v[82:97], v[232:235], v[106:109], v[82:97]
	v_mfma_f32_32x32x16_bf16 v[66:81], v[236:239], v[106:109], v[66:81]
	ds_read_b128 v[232:235], v196 offset:8192
	ds_read_b128 v[236:239], v196 offset:12288
	s_waitcnt lgkmcnt(0)
	v_mfma_f32_32x32x16_bf16 v[82:97], v[232:235], v[102:105], v[82:97]
	v_mfma_f32_32x32x16_bf16 v[66:81], v[236:239], v[102:105], v[66:81]
	ds_read_b128 v[232:235], v199 offset:8192
	ds_read_b128 v[236:239], v199 offset:12288
	s_waitcnt lgkmcnt(0)
	v_mfma_f32_32x32x16_bf16 v[82:97], v[232:235], v[98:101], v[82:97]
	v_exp_f32_e32 v232, v154
	v_exp_f32_e32 v233, v155
	v_exp_f32_e32 v234, v152
	v_exp_f32_e32 v235, v153
	v_add_f32_e32 v146, v232, v146
	v_add_f32_e32 v146, v233, v146
	v_add_f32_e32 v146, v234, v146
	v_mfma_f32_32x32x16_bf16 v[66:81], v[236:239], v[98:101], v[66:81]
	v_exp_f32_e32 v236, v150
	v_exp_f32_e32 v237, v151
	v_exp_f32_e32 v238, v148
	v_exp_f32_e32 v239, v149
	v_add_f32_e32 v146, v235, v146
	v_add_f32_e32 v146, v236, v146
	v_add_f32_e32 v146, v237, v146
	v_add_f32_e32 v146, v238, v146
	v_add_f32_e32 v146, v239, v146
	v_add_f32_e32 v146, v240, v146
	v_add_f32_e32 v162, v241, v146
	v_mov_b32_e32 v163, v162
	s_nop 1
	v_permlane32_swap_b32_e32 v162, v163
	v_cvt_pk_bf16_f32 v146, v229, v231
	v_cvt_pk_bf16_f32 v147, v227, v230
	v_cvt_pk_bf16_f32 v148, v226, v228
	v_cvt_pk_bf16_f32 v149, v224, v225
	v_cvt_pk_bf16_f32 v150, v221, v223
	v_cvt_pk_bf16_f32 v151, v220, v222
	v_cvt_pk_bf16_f32 v152, v217, v219
	v_cvt_pk_bf16_f32 v153, v216, v218
	v_cvt_pk_bf16_f32 v154, v164, v165
	v_cvt_pk_bf16_f32 v155, v197, v215
	v_cvt_pk_bf16_f32 v156, v156, v157
	v_cvt_pk_bf16_f32 v157, v232, v233
	v_cvt_pk_bf16_f32 v216, v234, v235
	v_cvt_pk_bf16_f32 v217, v236, v237
	v_cvt_pk_bf16_f32 v218, v238, v239
	v_cvt_pk_bf16_f32 v219, v240, v241
	s_nop 0
	v_permlane32_swap_b32_e32 v146, v148
	v_permlane32_swap_b32_e32 v147, v149
	v_permlane32_swap_b32_e32 v150, v152
	v_permlane32_swap_b32_e32 v151, v153
	v_permlane32_swap_b32_e32 v154, v156
	v_permlane32_swap_b32_e32 v155, v157
	v_permlane32_swap_b32_e32 v216, v218
	v_permlane32_swap_b32_e32 v217, v219
	s_lshl_b32 s24, s17, 14
	v_add_u32_e32 v197, s24, v200
	ds_read_b64_tr_b16 v[220:221], v197 offset:0
	ds_read_b64_tr_b16 v[222:223], v197 offset:0x800
	ds_read_b64_tr_b16 v[224:225], v197 offset:0x1000
	ds_read_b64_tr_b16 v[226:227], v197 offset:0x1800
	ds_read_b64_tr_b16 v[228:229], v197 offset:0x2000
	ds_read_b64_tr_b16 v[230:231], v197 offset:0x2800
	ds_read_b64_tr_b16 v[232:233], v197 offset:0x3000
	ds_read_b64_tr_b16 v[234:235], v197 offset:0x3800
	s_waitcnt lgkmcnt(0)
	s_nop 0
	v_mfma_f32_32x32x16_bf16 v[2:17], v[146:149], v[220:223], v[2:17]
	ds_read_b64_tr_b16 v[220:221], v197 offset:0x200
	ds_read_b64_tr_b16 v[222:223], v197 offset:0xa00
	v_max_f32_e32 v164, v83, v83
	v_max_f32_e32 v165, v82, v82
	v_max_f32_e32 v164, v165, v164
	v_max3_f32 v164, v164, v84, v85
	v_max3_f32 v164, v164, v86, v87
	v_mfma_f32_32x32x16_bf16 v[2:17], v[150:153], v[224:227], v[2:17]
	ds_read_b64_tr_b16 v[224:225], v197 offset:0x1200
	ds_read_b64_tr_b16 v[226:227], v197 offset:0x1a00
	v_max3_f32 v164, v164, v88, v89
	v_max3_f32 v164, v164, v90, v91
	v_max3_f32 v164, v164, v92, v93
	v_max3_f32 v164, v164, v94, v95
	v_max3_f32 v164, v164, v96, v97
	v_mfma_f32_32x32x16_bf16 v[2:17], v[154:157], v[228:231], v[2:17]
	ds_read_b64_tr_b16 v[228:229], v197 offset:0x2200
	ds_read_b64_tr_b16 v[230:231], v197 offset:0x2a00
	ds_read_b64_tr_b16 v[236:237], v197 offset:0x3200
	ds_read_b64_tr_b16 v[238:239], v197 offset:0x3a00
	s_waitcnt lgkmcnt(0)
	v_mfma_f32_32x32x16_bf16 v[2:17], v[216:219], v[232:235], v[2:17]
	v_mfma_f32_32x32x16_bf16 v[50:65], v[146:149], v[220:223], v[50:65]
	v_max3_f32 v164, v164, v66, v67
	v_max3_f32 v164, v164, v68, v69
	v_max3_f32 v164, v164, v70, v71
	v_max3_f32 v164, v164, v72, v73
	v_max3_f32 v164, v164, v74, v75
	v_max3_f32 v164, v164, v76, v77
	v_max3_f32 v164, v164, v78, v79
	v_mfma_f32_32x32x16_bf16 v[50:65], v[150:153], v[224:227], v[50:65]
	v_max3_f32 v164, v164, v80, v81
	v_mov_b32_e32 v165, v164
	s_nop 1
	v_permlane32_swap_b32_e32 v164, v165
	ds_read_b64_tr_b16 v[220:221], v197 offset:0x400
	v_max_f32_e32 v165, v165, v165
	v_max_f32_e32 v164, v164, v164
	v_mfma_f32_32x32x16_bf16 v[50:65], v[154:157], v[228:231], v[50:65]
	ds_read_b64_tr_b16 v[222:223], v197 offset:0xc00
	v_max_f32_e32 v164, v164, v165
	v_max_f32_e32 v165, v202, v202
	ds_read_b64_tr_b16 v[224:225], v197 offset:0x1400
	v_max_f32_e32 v165, v165, v164
	ds_read_b64_tr_b16 v[226:227], v197 offset:0x1c00
	v_sub_f32_e32 v215, v164, v202
	v_mfma_f32_32x32x16_bf16 v[50:65], v[216:219], v[236:239], v[50:65]
	v_sub_f32_e32 v164, v202, v165
	ds_read_b64_tr_b16 v[228:229], v197 offset:0x2400
	v_mul_f32_e32 v164, 0x3dd53b94, v164
	ds_read_b64_tr_b16 v[230:231], v197 offset:0x2c00
	v_exp_f32_e32 v164, v164
	ds_read_b64_tr_b16 v[232:233], v197 offset:0x3400
	v_cmp_ge_f32_e32 vcc, s77, v215
	ds_read_b64_tr_b16 v[234:235], v197 offset:0x3c00
	s_cmp_eq_u64 vcc, exec
	s_waitcnt lgkmcnt(0)
	s_cselect_b64 s[4:5], -1, 0
	v_cndmask_b32_e64 v164, v164, 1.0, s[4:5]
	v_mfma_f32_32x32x16_bf16 v[34:49], v[146:149], v[220:223], v[34:49]
	ds_read_b64_tr_b16 v[220:221], v197 offset:0x600
	ds_read_b64_tr_b16 v[222:223], v197 offset:0xe00
	v_mfma_f32_32x32x16_bf16 v[34:49], v[150:153], v[224:227], v[34:49]
	ds_read_b64_tr_b16 v[224:225], v197 offset:0x1600
	ds_read_b64_tr_b16 v[226:227], v197 offset:0x1e00
	v_mfma_f32_32x32x16_bf16 v[34:49], v[154:157], v[228:231], v[34:49]
	ds_read_b64_tr_b16 v[228:229], v197 offset:0x2600
	ds_read_b64_tr_b16 v[230:231], v197 offset:0x2e00
	ds_read_b64_tr_b16 v[236:237], v197 offset:0x3600
	ds_read_b64_tr_b16 v[238:239], v197 offset:0x3e00
	s_waitcnt lgkmcnt(0)
	v_mfma_f32_32x32x16_bf16 v[34:49], v[216:219], v[232:235], v[34:49]
	v_mfma_f32_32x32x16_bf16 v[18:33], v[146:149], v[220:223], v[18:33]
	v_cmp_gt_f32_e32 vcc, 1.0, v164
	v_mfma_f32_32x32x16_bf16 v[18:33], v[150:153], v[224:227], v[18:33]
	v_mfma_f32_32x32x16_bf16 v[18:33], v[154:157], v[228:231], v[18:33]
	v_mfma_f32_32x32x16_bf16 v[18:33], v[216:219], v[236:239], v[18:33]
	s_cbranch_vccz .LBB0_547
	s_and_saveexec_b64 s[0:1], s[2:3]
	ds_write_b32 v170, v164 offset:128
	s_or_b64 exec, exec, s[0:1]
	s_waitcnt lgkmcnt(0)
	ds_read_b128 v[146:149], v158 offset:224
	ds_read_b128 v[150:153], v158 offset:192
	ds_read_b128 v[154:157], v158 offset:160
	ds_read_b128 v[216:219], v158 offset:128
	s_waitcnt lgkmcnt(0)
	v_pk_mul_f32 v[16:17], v[16:17], v[148:149]
	v_pk_mul_f32 v[12:13], v[12:13], v[152:153]
	v_pk_mul_f32 v[8:9], v[8:9], v[156:157]
	v_pk_mul_f32 v[4:5], v[4:5], v[218:219]
	v_pk_mul_f32 v[14:15], v[14:15], v[146:147]
	v_pk_mul_f32 v[10:11], v[10:11], v[150:151]
	v_pk_mul_f32 v[6:7], v[6:7], v[154:155]
	v_pk_mul_f32 v[2:3], v[2:3], v[216:217]
	v_pk_mul_f32 v[64:65], v[64:65], v[148:149]
	v_pk_mul_f32 v[60:61], v[60:61], v[152:153]
	v_pk_mul_f32 v[56:57], v[56:57], v[156:157]
	v_pk_mul_f32 v[52:53], v[52:53], v[218:219]
	v_pk_mul_f32 v[62:63], v[62:63], v[146:147]
	v_pk_mul_f32 v[58:59], v[58:59], v[150:151]
	v_pk_mul_f32 v[54:55], v[54:55], v[154:155]
	v_pk_mul_f32 v[50:51], v[50:51], v[216:217]
	v_pk_mul_f32 v[48:49], v[48:49], v[148:149]
	v_pk_mul_f32 v[44:45], v[44:45], v[152:153]
	v_pk_mul_f32 v[40:41], v[40:41], v[156:157]
	v_pk_mul_f32 v[36:37], v[36:37], v[218:219]
	v_pk_mul_f32 v[46:47], v[46:47], v[146:147]
	v_pk_mul_f32 v[42:43], v[42:43], v[150:151]
	v_pk_mul_f32 v[38:39], v[38:39], v[154:155]
	v_pk_mul_f32 v[34:35], v[34:35], v[216:217]
	v_pk_mul_f32 v[32:33], v[32:33], v[148:149]
	v_pk_mul_f32 v[28:29], v[28:29], v[152:153]
	v_pk_mul_f32 v[24:25], v[24:25], v[156:157]
	v_pk_mul_f32 v[20:21], v[20:21], v[218:219]
	v_pk_mul_f32 v[30:31], v[30:31], v[146:147]
	v_pk_mul_f32 v[26:27], v[26:27], v[150:151]
	v_pk_mul_f32 v[22:23], v[22:23], v[154:155]
	v_pk_mul_f32 v[18:19], v[18:19], v[216:217]

.LBB0_549:
	v_cndmask_b32_e64 v165, v165, v202, s[4:5]
	v_mul_f32_e32 v154, 0xbdd53b94, v165
	v_fmamk_f32 v82, v82, 0x3dd53b94, v154
	v_fmamk_f32 v83, v83, 0x3dd53b94, v154
	v_fmamk_f32 v84, v84, 0x3dd53b94, v154
	v_fmamk_f32 v85, v85, 0x3dd53b94, v154
	v_fmamk_f32 v86, v86, 0x3dd53b94, v154
	v_fmamk_f32 v87, v87, 0x3dd53b94, v154
	v_fmamk_f32 v88, v88, 0x3dd53b94, v154
	v_fmamk_f32 v89, v89, 0x3dd53b94, v154
	v_fmamk_f32 v90, v90, 0x3dd53b94, v154
	v_fmamk_f32 v91, v91, 0x3dd53b94, v154
	v_fmamk_f32 v92, v92, 0x3dd53b94, v154
	v_fmamk_f32 v93, v93, 0x3dd53b94, v154
	v_fmamk_f32 v94, v94, 0x3dd53b94, v154
	v_fmamk_f32 v95, v95, 0x3dd53b94, v154
	v_fmamk_f32 v96, v96, 0x3dd53b94, v154
	v_fmamk_f32 v97, v97, 0x3dd53b94, v154
	v_fmamk_f32 v202, v69, 0x3dd53b94, v154
	v_fmamk_f32 v215, v70, 0x3dd53b94, v154
	v_fmamk_f32 v232, v79, 0x3dd53b94, v154
	v_fmamk_f32 v233, v80, 0x3dd53b94, v154
	v_fmamk_f32 v155, v66, 0x3dd53b94, v154
	v_fmamk_f32 v156, v67, 0x3dd53b94, v154
	v_fmamk_f32 v157, v68, 0x3dd53b94, v154
	v_fmamk_f32 v216, v71, 0x3dd53b94, v154
	v_fmamk_f32 v217, v72, 0x3dd53b94, v154
	v_fmamk_f32 v218, v73, 0x3dd53b94, v154
	v_fmamk_f32 v219, v74, 0x3dd53b94, v154
	v_fmamk_f32 v220, v75, 0x3dd53b94, v154
	v_fmamk_f32 v221, v76, 0x3dd53b94, v154
	v_fmamk_f32 v222, v77, 0x3dd53b94, v154
	v_fmamk_f32 v223, v78, 0x3dd53b94, v154
	v_exp_f32_e32 v224, v82
	v_exp_f32_e32 v225, v83
	v_exp_f32_e32 v226, v84
	v_exp_f32_e32 v227, v85
	v_exp_f32_e32 v228, v86
	v_exp_f32_e32 v229, v87
	v_exp_f32_e32 v230, v88
	v_exp_f32_e32 v231, v89
	v_exp_f32_e32 v234, v90
	v_exp_f32_e32 v235, v91
	v_exp_f32_e32 v236, v92
	v_exp_f32_e32 v237, v93
	v_exp_f32_e32 v238, v94
	v_exp_f32_e32 v239, v95
	v_exp_f32_e32 v240, v96
	v_exp_f32_e32 v241, v97
	v_fmac_f32_e32 v154, 0x3dd53b94, v81
	ds_read_b128 v[66:69], v174 offset:32768
	ds_read_b128 v[70:73], v174 offset:40960
	ds_read_b128 v[146:149], v176 offset:32768
	ds_read_b128 v[150:153], v176 offset:40960
	v_exp_f32_e32 v155, v155
	v_exp_f32_e32 v156, v156
	s_waitcnt lgkmcnt(0)
	v_mfma_f32_32x32x16_bf16 v[82:97], v[66:69], v[142:145], 0
	v_exp_f32_e32 v157, v157
	v_exp_f32_e32 v202, v202
	v_exp_f32_e32 v215, v215
	v_exp_f32_e32 v216, v216
	v_exp_f32_e32 v217, v217
	v_exp_f32_e32 v218, v218
	v_exp_f32_e32 v219, v219
	v_mfma_f32_32x32x16_bf16 v[66:81], v[70:73], v[142:145], 0
	v_exp_f32_e32 v220, v220
	v_exp_f32_e32 v221, v221
	v_exp_f32_e32 v222, v222
	v_exp_f32_e32 v223, v223
	v_exp_f32_e32 v242, v232
	v_exp_f32_e32 v243, v233
	v_exp_f32_e32 v244, v154
	v_mfma_f32_32x32x16_bf16 v[82:97], v[146:149], v[138:141], v[82:97]
	v_mfma_f32_32x32x16_bf16 v[66:81], v[150:153], v[138:141], v[66:81]
	ds_read_b128 v[146:149], v178 offset:32768
	ds_read_b128 v[150:153], v178 offset:40960
	s_cmp_lg_u32 s98, 0
	s_cbranch_scc1 .Lattn_mla_nopf
	s_add_u32 s0, s38, s20
	s_addc_u32 s1, s39, s21
	s_add_u32 s100, s0, s42
	s_addc_u32 s101, s1, s43
	s_mov_b32 m0, s93
	v_lshl_add_u64 v[254:255], v[246:247], 0, s[100:101]
	global_load_lds_dwordx4 v[254:255], off
	s_add_u32 s100, s0, s46
	s_addc_u32 s101, s1, s47
	s_mov_b32 m0, s94
	v_lshl_add_u64 v[254:255], v[246:247], 0, s[100:101]
	global_load_lds_dwordx4 v[254:255], off
	s_add_u32 s100, s0, s44
	s_addc_u32 s101, s1, s45
	s_add_i32 s98, s89, s24
	s_mov_b32 m0, s98
	v_lshl_add_u64 v[254:255], v[248:249], 0, s[100:101]
	global_load_lds_dwordx4 v[254:255], off
	s_add_u32 s100, s0, s50
	s_addc_u32 s101, s1, s51
	s_add_i32 m0, s98, 0x2000
	v_lshl_add_u64 v[254:255], v[248:249], 0, s[100:101]
	global_load_lds_dwordx4 v[254:255], off
	s_add_u32 s0, s38, s88
	s_addc_u32 s1, s39, s87
	s_add_u32 s0, s0, s58
	s_addc_u32 s1, s1, s59
	s_mov_b32 m0, s95
	v_lshl_add_u64 v[254:255], v[250:251], 0, s[0:1]
	global_load_lds_dwordx4 v[254:255], off
.Lattn_mla_nopf:
	s_waitcnt lgkmcnt(0)
	v_mfma_f32_32x32x16_bf16 v[82:97], v[146:149], v[134:137], v[82:97]
	v_mfma_f32_32x32x16_bf16 v[66:81], v[150:153], v[134:137], v[66:81]
	ds_read_b128 v[146:149], v180 offset:32768
	ds_read_b128 v[150:153], v180 offset:40960
	s_waitcnt lgkmcnt(0)
	v_mfma_f32_32x32x16_bf16 v[82:97], v[146:149], v[130:133], v[82:97]
	v_mfma_f32_32x32x16_bf16 v[66:81], v[150:153], v[130:133], v[66:81]
	ds_read_b128 v[146:149], v182 offset:32768
	ds_read_b128 v[150:153], v182 offset:40960
	s_waitcnt lgkmcnt(0)
	v_mfma_f32_32x32x16_bf16 v[82:97], v[146:149], v[126:129], v[82:97]
	v_mfma_f32_32x32x16_bf16 v[66:81], v[150:153], v[126:129], v[66:81]
	ds_read_b128 v[146:149], v186 offset:32768
	ds_read_b128 v[150:153], v186 offset:40960
	s_waitcnt lgkmcnt(0)
	v_mfma_f32_32x32x16_bf16 v[82:97], v[146:149], v[122:125], v[82:97]
	v_mfma_f32_32x32x16_bf16 v[66:81], v[150:153], v[122:125], v[66:81]
	ds_read_b128 v[146:149], v188 offset:32768
	ds_read_b128 v[150:153], v188 offset:40960
	s_waitcnt lgkmcnt(0)
	v_mfma_f32_32x32x16_bf16 v[82:97], v[146:149], v[118:121], v[82:97]
	v_mfma_f32_32x32x16_bf16 v[66:81], v[150:153], v[118:121], v[66:81]
	ds_read_b128 v[146:149], v190 offset:32768
	ds_read_b128 v[150:153], v190 offset:40960
	s_waitcnt lgkmcnt(0)
	v_mfma_f32_32x32x16_bf16 v[82:97], v[146:149], v[114:117], v[82:97]
	v_mfma_f32_32x32x16_bf16 v[66:81], v[150:153], v[114:117], v[66:81]
	ds_read_b128 v[146:149], v192
	ds_read_b128 v[150:153], v192 offset:4096
	s_waitcnt lgkmcnt(0)
	v_mfma_f32_32x32x16_bf16 v[82:97], v[146:149], v[110:113], v[82:97]
	v_mfma_f32_32x32x16_bf16 v[66:81], v[150:153], v[110:113], v[66:81]
	ds_read_b128 v[146:149], v194
	ds_read_b128 v[150:153], v194 offset:4096
	s_waitcnt lgkmcnt(0)
	v_mfma_f32_32x32x16_bf16 v[82:97], v[146:149], v[106:109], v[82:97]
	v_mfma_f32_32x32x16_bf16 v[66:81], v[150:153], v[106:109], v[66:81]
	ds_read_b128 v[146:149], v196
	ds_read_b128 v[150:153], v196 offset:4096
	s_waitcnt lgkmcnt(0)
	v_mfma_f32_32x32x16_bf16 v[82:97], v[146:149], v[102:105], v[82:97]
	v_mfma_f32_32x32x16_bf16 v[66:81], v[150:153], v[102:105], v[66:81]
	ds_read_b128 v[146:149], v199
	ds_read_b128 v[150:153], v199 offset:4096
	s_waitcnt lgkmcnt(0)
	v_mfma_f32_32x32x16_bf16 v[82:97], v[146:149], v[98:101], v[82:97]
	v_add_f32_e32 v146, 0, v224
	v_add_f32_e32 v146, v225, v146
	v_add_f32_e32 v146, v226, v146
	v_add_f32_e32 v146, v227, v146
	v_add_f32_e32 v146, v228, v146
	v_add_f32_e32 v146, v229, v146
	v_add_f32_e32 v146, v230, v146
	v_add_f32_e32 v146, v231, v146
	v_add_f32_e32 v146, v234, v146
	v_add_f32_e32 v146, v235, v146
	v_add_f32_e32 v146, v236, v146
	v_add_f32_e32 v146, v237, v146
	v_add_f32_e32 v146, v238, v146
	v_add_f32_e32 v146, v239, v146
	v_add_f32_e32 v146, v240, v146
	v_add_f32_e32 v146, v241, v146
	v_add_f32_e32 v146, v155, v146
	v_add_f32_e32 v146, v156, v146
	v_add_f32_e32 v146, v157, v146
	v_add_f32_e32 v146, v202, v146
	v_add_f32_e32 v146, v215, v146
	v_add_f32_e32 v146, v216, v146
	v_add_f32_e32 v146, v217, v146
	v_add_f32_e32 v146, v218, v146
	v_add_f32_e32 v146, v219, v146
	v_add_f32_e32 v146, v220, v146
	v_mfma_f32_32x32x16_bf16 v[66:81], v[150:153], v[98:101], v[66:81]
	v_add_f32_e32 v146, v221, v146
	v_add_f32_e32 v146, v222, v146
	v_add_f32_e32 v146, v223, v146
	v_add_f32_e32 v146, v242, v146
	v_add_f32_e32 v146, v243, v146
	v_add_f32_e32 v232, v244, v146
	v_mov_b32_e32 v233, v232
	s_nop 1
	v_permlane32_swap_b32_e32 v232, v233
	v_cvt_pk_bf16_f32 v146, v224, v225
	v_cvt_pk_bf16_f32 v147, v226, v227
	v_cvt_pk_bf16_f32 v148, v228, v229
	v_cvt_pk_bf16_f32 v149, v230, v231
	v_cvt_pk_bf16_f32 v150, v234, v235
	v_cvt_pk_bf16_f32 v151, v236, v237
	v_cvt_pk_bf16_f32 v152, v238, v239
	v_cvt_pk_bf16_f32 v153, v240, v241
	v_cvt_pk_bf16_f32 v154, v155, v156
	v_cvt_pk_bf16_f32 v155, v157, v202
	v_cvt_pk_bf16_f32 v156, v215, v216
	v_cvt_pk_bf16_f32 v157, v217, v218
	v_cvt_pk_bf16_f32 v216, v219, v220
	v_cvt_pk_bf16_f32 v217, v221, v222
	v_cvt_pk_bf16_f32 v218, v223, v242
	v_cvt_pk_bf16_f32 v219, v243, v244
	s_nop 0
	v_permlane32_swap_b32_e32 v146, v148
	v_permlane32_swap_b32_e32 v147, v149
	v_permlane32_swap_b32_e32 v150, v152
	v_permlane32_swap_b32_e32 v151, v153
	v_permlane32_swap_b32_e32 v154, v156
	v_permlane32_swap_b32_e32 v155, v157
	v_permlane32_swap_b32_e32 v216, v218
	v_permlane32_swap_b32_e32 v217, v219
	v_lshl_add_u32 v242, s23, 14, v200
	ds_read_b64_tr_b16 v[220:221], v242 offset:0
	ds_read_b64_tr_b16 v[222:223], v242 offset:0x800
	ds_read_b64_tr_b16 v[224:225], v242 offset:0x1000
	ds_read_b64_tr_b16 v[226:227], v242 offset:0x1800
	ds_read_b64_tr_b16 v[228:229], v242 offset:0x2000
	ds_read_b64_tr_b16 v[230:231], v242 offset:0x2800
	ds_read_b64_tr_b16 v[234:235], v242 offset:0x3000
	ds_read_b64_tr_b16 v[236:237], v242 offset:0x3800
	s_waitcnt lgkmcnt(0)
	s_nop 0
	v_mfma_f32_32x32x16_bf16 v[2:17], v[146:149], v[220:223], v[2:17]
	ds_read_b64_tr_b16 v[220:221], v242 offset:0x200
	ds_read_b64_tr_b16 v[222:223], v242 offset:0xa00
	v_max_f32_e32 v202, v83, v83
	v_max_f32_e32 v215, v82, v82
	v_max_f32_e32 v202, v215, v202
	v_max3_f32 v202, v202, v84, v85
	v_max3_f32 v202, v202, v86, v87
	v_mfma_f32_32x32x16_bf16 v[2:17], v[150:153], v[224:227], v[2:17]
	ds_read_b64_tr_b16 v[224:225], v242 offset:0x1200
	ds_read_b64_tr_b16 v[226:227], v242 offset:0x1a00
	v_max3_f32 v202, v202, v88, v89
	v_max3_f32 v202, v202, v90, v91
	v_max3_f32 v202, v202, v92, v93
	v_max3_f32 v202, v202, v94, v95
	v_max3_f32 v202, v202, v96, v97
	v_mfma_f32_32x32x16_bf16 v[2:17], v[154:157], v[228:231], v[2:17]
	ds_read_b64_tr_b16 v[228:229], v242 offset:0x2200
	ds_read_b64_tr_b16 v[230:231], v242 offset:0x2a00
	ds_read_b64_tr_b16 v[238:239], v242 offset:0x3200
	ds_read_b64_tr_b16 v[240:241], v242 offset:0x3a00
	s_waitcnt lgkmcnt(0)
	v_mfma_f32_32x32x16_bf16 v[2:17], v[216:219], v[234:237], v[2:17]
	v_mfma_f32_32x32x16_bf16 v[50:65], v[146:149], v[220:223], v[50:65]
	v_max3_f32 v202, v202, v66, v67
	v_max3_f32 v202, v202, v68, v69
	v_max3_f32 v202, v202, v70, v71
	v_max3_f32 v202, v202, v72, v73
	v_max3_f32 v202, v202, v74, v75
	v_max3_f32 v202, v202, v76, v77
	v_max3_f32 v202, v202, v78, v79
	v_mfma_f32_32x32x16_bf16 v[50:65], v[150:153], v[224:227], v[50:65]
	v_max3_f32 v202, v202, v80, v81
	v_mov_b32_e32 v215, v202
	s_nop 1
	v_permlane32_swap_b32_e32 v202, v215
	v_max_f32_e32 v215, v215, v215
	v_max_f32_e32 v202, v202, v202
	v_max_f32_e32 v202, v202, v215
	v_max_f32_e32 v220, v165, v165
	v_sub_f32_e32 v215, v202, v165
	v_max_f32_e32 v202, v220, v202
	v_sub_f32_e32 v220, v165, v202
	v_mul_f32_e32 v220, 0x3dd53b94, v220
	v_mfma_f32_32x32x16_bf16 v[50:65], v[154:157], v[228:231], v[50:65]
	v_exp_f32_e32 v220, v220
	v_cmp_ge_f32_e32 vcc, s77, v215
	s_cmp_eq_u64 vcc, exec
	s_cselect_b64 s[4:5], -1, 0
	v_cndmask_b32_e64 v215, v220, 1.0, s[4:5]
	ds_read_b64_tr_b16 v[220:221], v242 offset:0x400
	ds_read_b64_tr_b16 v[222:223], v242 offset:0xc00
	ds_read_b64_tr_b16 v[224:225], v242 offset:0x1400
	v_mfma_f32_32x32x16_bf16 v[50:65], v[216:219], v[238:241], v[50:65]
	ds_read_b64_tr_b16 v[226:227], v242 offset:0x1c00
	ds_read_b64_tr_b16 v[228:229], v242 offset:0x2400
	ds_read_b64_tr_b16 v[230:231], v242 offset:0x2c00
	ds_read_b64_tr_b16 v[234:235], v242 offset:0x3400
	ds_read_b64_tr_b16 v[236:237], v242 offset:0x3c00
	s_waitcnt lgkmcnt(0)
	v_mfma_f32_32x32x16_bf16 v[34:49], v[146:149], v[220:223], v[34:49]
	ds_read_b64_tr_b16 v[220:221], v242 offset:0x600
	ds_read_b64_tr_b16 v[222:223], v242 offset:0xe00
	v_mfma_f32_32x32x16_bf16 v[34:49], v[150:153], v[224:227], v[34:49]
	ds_read_b64_tr_b16 v[224:225], v242 offset:0x1600
	ds_read_b64_tr_b16 v[226:227], v242 offset:0x1e00
	v_mfma_f32_32x32x16_bf16 v[34:49], v[154:157], v[228:231], v[34:49]
	ds_read_b64_tr_b16 v[228:229], v242 offset:0x2600
	ds_read_b64_tr_b16 v[230:231], v242 offset:0x2e00
	ds_read_b64_tr_b16 v[238:239], v242 offset:0x3600
	ds_read_b64_tr_b16 v[240:241], v242 offset:0x3e00
	s_waitcnt lgkmcnt(0)
	v_mfma_f32_32x32x16_bf16 v[34:49], v[216:219], v[234:237], v[34:49]
	v_mfma_f32_32x32x16_bf16 v[18:33], v[146:149], v[220:223], v[18:33]
	v_cmp_gt_f32_e32 vcc, 1.0, v215
	v_mfma_f32_32x32x16_bf16 v[18:33], v[150:153], v[224:227], v[18:33]
	v_mfma_f32_32x32x16_bf16 v[18:33], v[154:157], v[228:231], v[18:33]
	v_mfma_f32_32x32x16_bf16 v[18:33], v[216:219], v[238:241], v[18:33]
	s_cbranch_vccz .LBB0_553
	s_and_saveexec_b64 s[0:1], s[2:3]
	ds_write_b32 v170, v215 offset:128
	s_or_b64 exec, exec, s[0:1]
	s_waitcnt lgkmcnt(0)
	ds_read_b128 v[146:149], v158 offset:224
	ds_read_b128 v[150:153], v158 offset:192
	ds_read_b128 v[154:157], v158 offset:160
	ds_read_b128 v[216:219], v158 offset:128
	s_waitcnt lgkmcnt(0)
	v_pk_mul_f32 v[16:17], v[16:17], v[148:149]
	v_pk_mul_f32 v[12:13], v[12:13], v[152:153]
	v_pk_mul_f32 v[8:9], v[8:9], v[156:157]
	v_pk_mul_f32 v[4:5], v[4:5], v[218:219]
	v_pk_mul_f32 v[14:15], v[14:15], v[146:147]
	v_pk_mul_f32 v[10:11], v[10:11], v[150:151]
	v_pk_mul_f32 v[6:7], v[6:7], v[154:155]
	v_pk_mul_f32 v[2:3], v[2:3], v[216:217]
	v_pk_mul_f32 v[64:65], v[64:65], v[148:149]
	v_pk_mul_f32 v[60:61], v[60:61], v[152:153]
	v_pk_mul_f32 v[56:57], v[56:57], v[156:157]
	v_pk_mul_f32 v[52:53], v[52:53], v[218:219]
	v_pk_mul_f32 v[62:63], v[62:63], v[146:147]
	v_pk_mul_f32 v[58:59], v[58:59], v[150:151]
	v_pk_mul_f32 v[54:55], v[54:55], v[154:155]
	v_pk_mul_f32 v[50:51], v[50:51], v[216:217]
	v_pk_mul_f32 v[48:49], v[48:49], v[148:149]
	v_pk_mul_f32 v[44:45], v[44:45], v[152:153]
	v_pk_mul_f32 v[40:41], v[40:41], v[156:157]
	v_pk_mul_f32 v[36:37], v[36:37], v[218:219]
	v_pk_mul_f32 v[46:47], v[46:47], v[146:147]
	v_pk_mul_f32 v[42:43], v[42:43], v[150:151]
	v_pk_mul_f32 v[38:39], v[38:39], v[154:155]
	v_pk_mul_f32 v[34:35], v[34:35], v[216:217]
	v_pk_mul_f32 v[32:33], v[32:33], v[148:149]
	v_pk_mul_f32 v[28:29], v[28:29], v[152:153]
	v_pk_mul_f32 v[24:25], v[24:25], v[156:157]
	v_pk_mul_f32 v[20:21], v[20:21], v[218:219]
	v_pk_mul_f32 v[30:31], v[30:31], v[146:147]
	v_pk_mul_f32 v[26:27], v[26:27], v[150:151]
	v_pk_mul_f32 v[22:23], v[22:23], v[154:155]
	v_pk_mul_f32 v[18:19], v[18:19], v[216:217]

.LBB0_555:
	ds_read_b128 v[66:69], v174 offset:49152
	ds_read_b128 v[70:73], v174 offset:57344
	v_exp_f32_e32 v164, v164
	v_exp_f32_e32 v165, v165
	v_exp_f32_e32 v162, v162
	s_waitcnt lgkmcnt(1)
	v_mfma_f32_32x32x16_bf16 v[82:97], v[66:69], v[142:145], 0
	v_exp_f32_e32 v163, v163
	v_exp_f32_e32 v156, v156
	v_exp_f32_e32 v150, v150
	v_exp_f32_e32 v151, v151
	s_waitcnt lgkmcnt(0)
	v_mfma_f32_32x32x16_bf16 v[66:81], v[70:73], v[142:145], 0
	ds_read_b128 v[142:145], v176 offset:49152
	ds_read_b128 v[172:175], v176 offset:57344
	s_waitcnt lgkmcnt(1)
	v_mfma_f32_32x32x16_bf16 v[82:97], v[142:145], v[138:141], v[82:97]
	s_waitcnt lgkmcnt(0)
	v_mfma_f32_32x32x16_bf16 v[66:81], v[172:175], v[138:141], v[66:81]
	ds_read_b128 v[138:141], v178 offset:49152
	ds_read_b128 v[142:145], v178 offset:57344
	s_waitcnt lgkmcnt(1)
	v_mfma_f32_32x32x16_bf16 v[82:97], v[138:141], v[134:137], v[82:97]
	s_waitcnt lgkmcnt(0)
	v_mfma_f32_32x32x16_bf16 v[66:81], v[142:145], v[134:137], v[66:81]
	ds_read_b128 v[134:137], v180 offset:49152
	ds_read_b128 v[138:141], v180 offset:57344
	s_waitcnt lgkmcnt(1)
	v_mfma_f32_32x32x16_bf16 v[82:97], v[134:137], v[130:133], v[82:97]
	s_waitcnt lgkmcnt(0)
	v_mfma_f32_32x32x16_bf16 v[66:81], v[138:141], v[130:133], v[66:81]
	ds_read_b128 v[130:133], v182 offset:49152
	ds_read_b128 v[134:137], v182 offset:57344
	s_waitcnt lgkmcnt(1)
	v_mfma_f32_32x32x16_bf16 v[82:97], v[130:133], v[126:129], v[82:97]
	s_waitcnt lgkmcnt(0)
	v_mfma_f32_32x32x16_bf16 v[66:81], v[134:137], v[126:129], v[66:81]
	ds_read_b128 v[126:129], v186 offset:49152
	ds_read_b128 v[130:133], v186 offset:57344
	ds_read_b128 v[134:137], v188 offset:49152
	ds_read_b128 v[138:141], v188 offset:57344
	s_waitcnt lgkmcnt(3)
	v_mfma_f32_32x32x16_bf16 v[82:97], v[126:129], v[122:125], v[82:97]
	ds_read_b128 v[126:129], v190 offset:49152
	ds_read_b128 v[142:145], v190 offset:57344
	ds_read_b128 v[172:175], v192 offset:8192
	ds_read_b128 v[176:179], v192 offset:12288
	ds_read_b128 v[180:183], v194 offset:8192
	ds_read_b128 v[186:189], v194 offset:12288
	ds_read_b128 v[190:193], v196 offset:8192
	ds_read_b128 v[204:207], v196 offset:12288
	s_waitcnt lgkmcnt(10)
	v_mfma_f32_32x32x16_bf16 v[66:81], v[130:133], v[122:125], v[66:81]
	ds_read_b128 v[122:125], v199 offset:8192
	ds_read_b128 v[130:133], v199 offset:12288
	s_waitcnt lgkmcnt(11)
	v_mfma_f32_32x32x16_bf16 v[82:97], v[134:137], v[118:121], v[82:97]
	v_exp_f32_e32 v134, v157
	v_exp_f32_e32 v135, v154
	v_exp_f32_e32 v136, v155
	v_exp_f32_e32 v137, v152
	v_exp_f32_e32 v152, v153
	s_waitcnt lgkmcnt(10)
	v_mfma_f32_32x32x16_bf16 v[66:81], v[138:141], v[118:121], v[66:81]
	v_add_f32_e32 v118, 0, v229
	v_add_f32_e32 v118, v231, v118
	v_add_f32_e32 v118, v227, v118
	v_add_f32_e32 v118, v230, v118
	v_add_f32_e32 v118, v226, v118
	v_add_f32_e32 v118, v228, v118
	v_add_f32_e32 v118, v224, v118
	s_waitcnt lgkmcnt(9)
	v_mfma_f32_32x32x16_bf16 v[82:97], v[126:129], v[114:117], v[82:97]
	v_add_f32_e32 v118, v225, v118
	v_add_f32_e32 v118, v221, v118
	v_add_f32_e32 v118, v223, v118
	v_exp_f32_e32 v120, v148
	v_exp_f32_e32 v121, v149
	v_exp_f32_e32 v138, v146
	v_exp_f32_e32 v139, v147
	s_waitcnt lgkmcnt(8)
	v_mfma_f32_32x32x16_bf16 v[66:81], v[142:145], v[114:117], v[66:81]
	v_add_f32_e32 v114, v220, v118
	v_add_f32_e32 v114, v222, v114
	v_add_f32_e32 v114, v217, v114
	v_add_f32_e32 v114, v219, v114
	v_add_f32_e32 v114, v216, v114
	v_add_f32_e32 v114, v218, v114
	v_add_f32_e32 v114, v164, v114
	s_waitcnt lgkmcnt(7)
	v_mfma_f32_32x32x16_bf16 v[82:97], v[172:175], v[110:113], v[82:97]
	v_add_f32_e32 v114, v165, v114
	v_add_f32_e32 v114, v162, v114
	v_add_f32_e32 v114, v163, v114
	v_add_f32_e32 v114, v156, v114
	v_add_f32_e32 v114, v134, v114
	v_add_f32_e32 v114, v135, v114
	v_add_f32_e32 v114, v136, v114
	s_waitcnt lgkmcnt(6)
	v_mfma_f32_32x32x16_bf16 v[66:81], v[176:179], v[110:113], v[66:81]
	v_add_f32_e32 v110, v137, v114
	v_add_f32_e32 v110, v152, v110
	v_add_f32_e32 v110, v150, v110
	v_add_f32_e32 v110, v151, v110
	v_add_f32_e32 v110, v120, v110
	v_add_f32_e32 v110, v121, v110
	v_add_f32_e32 v110, v138, v110
	s_waitcnt lgkmcnt(5)
	v_mfma_f32_32x32x16_bf16 v[82:97], v[180:183], v[106:109], v[82:97]
	v_add_f32_e32 v110, v139, v110
	v_mov_b32_e32 v111, v110
	s_nop 1
	v_permlane32_swap_b32_e32 v110, v111
	v_cvt_pk_bf16_f32 v112, v229, v231
	v_cvt_pk_bf16_f32 v113, v227, v230
	v_cvt_pk_bf16_f32 v114, v226, v228
	s_waitcnt lgkmcnt(4)
	v_mfma_f32_32x32x16_bf16 v[66:81], v[186:189], v[106:109], v[66:81]
	v_cvt_pk_bf16_f32 v115, v224, v225
	v_cvt_pk_bf16_f32 v106, v221, v223
	v_cvt_pk_bf16_f32 v107, v220, v222
	v_cvt_pk_bf16_f32 v108, v217, v219
	v_cvt_pk_bf16_f32 v109, v216, v218
	v_cvt_pk_bf16_f32 v116, v164, v165
	v_cvt_pk_bf16_f32 v117, v162, v163
	s_waitcnt lgkmcnt(3)
	v_mfma_f32_32x32x16_bf16 v[82:97], v[190:193], v[102:105], v[82:97]
	v_cvt_pk_bf16_f32 v118, v156, v134
	v_cvt_pk_bf16_f32 v119, v135, v136
	v_permlane32_swap_b32_e32 v112, v114
	v_permlane32_swap_b32_e32 v113, v115
	v_permlane32_swap_b32_e32 v106, v108
	s_waitcnt lgkmcnt(2)
	v_mfma_f32_32x32x16_bf16 v[66:81], v[204:207], v[102:105], v[66:81]
	v_cvt_pk_bf16_f32 v102, v137, v152
	v_cvt_pk_bf16_f32 v103, v150, v151
	v_cvt_pk_bf16_f32 v104, v120, v121
	v_cvt_pk_bf16_f32 v105, v138, v139
	v_permlane32_swap_b32_e32 v107, v109
	v_permlane32_swap_b32_e32 v116, v118
	s_waitcnt lgkmcnt(1)
	v_mfma_f32_32x32x16_bf16 v[82:97], v[122:125], v[98:101], v[82:97]
	v_permlane32_swap_b32_e32 v117, v119
	v_permlane32_swap_b32_e32 v102, v104
	v_permlane32_swap_b32_e32 v103, v105
	s_waitcnt lgkmcnt(0)
	v_mfma_f32_32x32x16_bf16 v[66:81], v[130:133], v[98:101], v[66:81]
	v_add_u32_e32 v140, s18, v200
	ds_read_b64_tr_b16 v[98:99], v140 offset:0
	ds_read_b64_tr_b16 v[100:101], v140 offset:0x800
	ds_read_b64_tr_b16 v[120:121], v140 offset:0x1000
	ds_read_b64_tr_b16 v[122:123], v140 offset:0x1800
	ds_read_b64_tr_b16 v[124:125], v140 offset:0x2000
	ds_read_b64_tr_b16 v[126:127], v140 offset:0x2800
	ds_read_b64_tr_b16 v[128:129], v140 offset:0x3000
	ds_read_b64_tr_b16 v[130:131], v140 offset:0x3800
	s_waitcnt lgkmcnt(0)
	s_nop 0
	v_mfma_f32_32x32x16_bf16 v[2:17], v[112:115], v[98:101], v[2:17]
	s_nop 3
	v_max_f32_e32 v98, v83, v83
	v_max_f32_e32 v99, v82, v82
	v_max_f32_e32 v98, v99, v98
	v_max3_f32 v98, v98, v84, v85
	v_max3_f32 v98, v98, v86, v87
	v_max3_f32 v98, v98, v88, v89
	v_max3_f32 v98, v98, v90, v91
	v_mfma_f32_32x32x16_bf16 v[2:17], v[106:109], v[120:123], v[2:17]
	v_max3_f32 v98, v98, v92, v93
	v_max3_f32 v100, v98, v94, v95
	ds_read_b64_tr_b16 v[98:99], v140 offset:0x200
	v_max3_f32 v136, v100, v96, v97
	ds_read_b64_tr_b16 v[100:101], v140 offset:0xa00
	ds_read_b64_tr_b16 v[120:121], v140 offset:0x1200
	ds_read_b64_tr_b16 v[122:123], v140 offset:0x1a00
	v_mfma_f32_32x32x16_bf16 v[2:17], v[116:119], v[124:127], v[2:17]
	ds_read_b64_tr_b16 v[124:125], v140 offset:0x2200
	ds_read_b64_tr_b16 v[126:127], v140 offset:0x2a00
	ds_read_b64_tr_b16 v[132:133], v140 offset:0x3200
	ds_read_b64_tr_b16 v[134:135], v140 offset:0x3a00
	s_waitcnt lgkmcnt(0)
	v_mfma_f32_32x32x16_bf16 v[2:17], v[102:105], v[128:131], v[2:17]
	v_mfma_f32_32x32x16_bf16 v[50:65], v[112:115], v[98:101], v[50:65]
	v_max3_f32 v128, v136, v66, v67
	v_max3_f32 v128, v128, v68, v69
	v_max3_f32 v128, v128, v70, v71
	v_max3_f32 v128, v128, v72, v73
	v_max3_f32 v128, v128, v74, v75
	v_max3_f32 v128, v128, v76, v77
	v_max3_f32 v98, v128, v78, v79
	v_mfma_f32_32x32x16_bf16 v[50:65], v[106:109], v[120:123], v[50:65]
	v_max3_f32 v98, v98, v80, v81
	v_mov_b32_e32 v99, v98
	s_nop 1
	v_permlane32_swap_b32_e32 v98, v99
	ds_read_b64_tr_b16 v[120:121], v140 offset:0x400
	v_max_f32_e32 v99, v99, v99
	v_max_f32_e32 v98, v98, v98
	v_mfma_f32_32x32x16_bf16 v[50:65], v[116:119], v[124:127], v[50:65]
	ds_read_b64_tr_b16 v[122:123], v140 offset:0xc00
	v_max_f32_e32 v98, v98, v99
	v_max_f32_e32 v99, v202, v202
	ds_read_b64_tr_b16 v[124:125], v140 offset:0x1400
	v_max_f32_e32 v99, v99, v98
	ds_read_b64_tr_b16 v[126:127], v140 offset:0x1c00
	v_sub_f32_e32 v100, v98, v202
	v_mfma_f32_32x32x16_bf16 v[50:65], v[102:105], v[132:135], v[50:65]
	v_sub_f32_e32 v98, v202, v99
	ds_read_b64_tr_b16 v[128:129], v140 offset:0x2400
	v_mul_f32_e32 v98, 0x3dd53b94, v98
	ds_read_b64_tr_b16 v[130:131], v140 offset:0x2c00
	v_exp_f32_e32 v98, v98
	ds_read_b64_tr_b16 v[132:133], v140 offset:0x3400
	v_cmp_ge_f32_e32 vcc, s77, v100
	ds_read_b64_tr_b16 v[134:135], v140 offset:0x3c00
	s_cmp_eq_u64 vcc, exec
	s_waitcnt lgkmcnt(0)
	s_cselect_b64 s[4:5], -1, 0
	v_cndmask_b32_e64 v98, v98, 1.0, s[4:5]
	v_mfma_f32_32x32x16_bf16 v[34:49], v[112:115], v[120:123], v[34:49]
	ds_read_b64_tr_b16 v[120:121], v140 offset:0x600
	ds_read_b64_tr_b16 v[122:123], v140 offset:0xe00
	v_mfma_f32_32x32x16_bf16 v[34:49], v[106:109], v[124:127], v[34:49]
	ds_read_b64_tr_b16 v[124:125], v140 offset:0x1600
	ds_read_b64_tr_b16 v[126:127], v140 offset:0x1e00
	v_mfma_f32_32x32x16_bf16 v[34:49], v[116:119], v[128:131], v[34:49]
	ds_read_b64_tr_b16 v[128:129], v140 offset:0x2600
	ds_read_b64_tr_b16 v[130:131], v140 offset:0x2e00
	ds_read_b64_tr_b16 v[136:137], v140 offset:0x3600
	ds_read_b64_tr_b16 v[138:139], v140 offset:0x3e00
	s_waitcnt lgkmcnt(0)
	v_mfma_f32_32x32x16_bf16 v[34:49], v[102:105], v[132:135], v[34:49]
	v_mfma_f32_32x32x16_bf16 v[18:33], v[112:115], v[120:123], v[18:33]
	v_cmp_gt_f32_e32 vcc, 1.0, v98
	v_mfma_f32_32x32x16_bf16 v[18:33], v[106:109], v[124:127], v[18:33]
	v_mfma_f32_32x32x16_bf16 v[18:33], v[116:119], v[128:131], v[18:33]
	v_mfma_f32_32x32x16_bf16 v[18:33], v[102:105], v[136:139], v[18:33]
	s_cbranch_vccz .LBB0_559
	s_and_saveexec_b64 s[0:1], s[2:3]
	v_readlane_b32 s88, v253, 10
	v_readlane_b32 s89, v253, 11
	ds_write_b32 v170, v98 offset:128
	s_or_b64 exec, exec, s[0:1]
	s_waitcnt lgkmcnt(0)
	ds_read_b128 v[100:103], v158 offset:224
	ds_read_b128 v[104:107], v158 offset:192
	ds_read_b128 v[112:115], v158 offset:160
	ds_read_b128 v[116:119], v158 offset:128
	s_waitcnt lgkmcnt(3)
	v_pk_mul_f32 v[16:17], v[16:17], v[102:103]
	s_waitcnt lgkmcnt(2)
	v_pk_mul_f32 v[12:13], v[12:13], v[106:107]
	s_waitcnt lgkmcnt(1)
	v_pk_mul_f32 v[8:9], v[8:9], v[114:115]
	s_waitcnt lgkmcnt(0)
	v_pk_mul_f32 v[4:5], v[4:5], v[118:119]
	v_pk_mul_f32 v[14:15], v[14:15], v[100:101]
	v_pk_mul_f32 v[10:11], v[10:11], v[104:105]
	v_pk_mul_f32 v[6:7], v[6:7], v[112:113]
	v_pk_mul_f32 v[2:3], v[2:3], v[116:117]
	v_pk_mul_f32 v[64:65], v[64:65], v[102:103]
	v_pk_mul_f32 v[60:61], v[60:61], v[106:107]
	v_pk_mul_f32 v[56:57], v[56:57], v[114:115]
	v_pk_mul_f32 v[52:53], v[52:53], v[118:119]
	v_pk_mul_f32 v[62:63], v[62:63], v[100:101]
	v_pk_mul_f32 v[58:59], v[58:59], v[104:105]
	v_pk_mul_f32 v[54:55], v[54:55], v[112:113]
	v_pk_mul_f32 v[50:51], v[50:51], v[116:117]
	v_pk_mul_f32 v[48:49], v[48:49], v[102:103]
	v_pk_mul_f32 v[44:45], v[44:45], v[106:107]
	v_pk_mul_f32 v[40:41], v[40:41], v[114:115]
	v_pk_mul_f32 v[36:37], v[36:37], v[118:119]
	v_pk_mul_f32 v[46:47], v[46:47], v[100:101]
	v_pk_mul_f32 v[42:43], v[42:43], v[104:105]
	v_pk_mul_f32 v[38:39], v[38:39], v[112:113]
	v_pk_mul_f32 v[34:35], v[34:35], v[116:117]
	v_pk_mul_f32 v[32:33], v[32:33], v[102:103]
	v_pk_mul_f32 v[28:29], v[28:29], v[106:107]
	v_pk_mul_f32 v[24:25], v[24:25], v[114:115]
	v_pk_mul_f32 v[20:21], v[20:21], v[118:119]
	v_pk_mul_f32 v[30:31], v[30:31], v[100:101]
	v_pk_mul_f32 v[26:27], v[26:27], v[104:105]
	v_pk_mul_f32 v[22:23], v[22:23], v[112:113]
	v_pk_mul_f32 v[18:19], v[18:19], v[116:117]
	s_branch .LBB0_560
